# v27 with one static s_setprio 1 for waves 4-7 around their attention tile loop and all per-segment priority flips deleted
# speedup vs baseline: 1.0056x; 1.0056x over previous
; #define DMA(slot, t) do { \
;     __builtin_amdgcn_global_load_lds((const unsigned*)(Kg + (long)(t) * (64 * 256)), (LAS unsigned*)(L3 + K_OFF + (slot) * SHM_T + wid * 1024), 16, 0, 0); \
;     __builtin_amdgcn_global_load_lds((const unsigned*)(Vg + (long)(t) * 8192), (LAS unsigned*)(L3 + (slot) * SHM_T + wid * 1024), 16, 0, 0); } while (0)
; #define BAR() do { asm volatile("s_waitcnt lgkmcnt(0)" ::: "memory"); __builtin_amdgcn_s_barrier(); asm volatile("" ::: "memory"); } while (0)
; #define WAITV(n) asm volatile("s_waitcnt vmcnt(" #n ")" ::: "memory")
; #define QKT(P0, P1, b) qkt(P0, P1, nm, K_lds + (b) * SHM_T, qr, ko, c00, c01, c10, c11)
; __device__ __forceinline__ void partialSM_first(f32x16& p0, f32x16& p1, f32x16& nm) {
;   const float delta = max32(p0, p1) - PSHIFT;
;   for (int r = 0; r < 16; ++r) { p0[r] -= delta; p1[r] -= delta; nm[r] -= delta; }
;   for (int r = 0; r < 16; ++r) p0[r] = __builtin_amdgcn_exp2f(p0[r]);
; }
; __device__ __forceinline__ void body(const unsigned char* Q8b, const unsigned char* K8h, const unsigned char* VT8h, const bf16_t* Gb, bf16_t* Ob, int seq, char* lds, const int wid, ...
;     ...
;   if (!pre) { DMA(0, 0); DMA(1, 1); } else BAR();
;   DMA(2, 2);
;   WAITV(2); BAR();
;   QKT(pA0, pA1, 0); partialSM_first(pA0, pA1, nm);
.LBB0_371:
	s_mov_b32 m0, s76
	v_lshl_add_u64 v[2:3], v[220:221], 0, s[42:43]
	global_load_lds_dwordx4 v[2:3], off
	s_mov_b32 m0, s78
	v_lshl_add_u64 v[2:3], v[222:223], 0, s[38:39]
	global_load_lds_dwordx4 v[2:3], off
	s_waitcnt vmcnt(2)
	s_waitcnt lgkmcnt(0)
	s_barrier
	ds_read_b128 v[22:25], v243 offset:32768
	ds_read_b128 v[18:21], v242 offset:32768
	ds_read_b128 v[34:37], v242 offset:36864
	ds_read_b128 v[38:41], v243 offset:36864
	v_mov_b64_e32 v[2:3], s[8:9]
	v_mov_b64_e32 v[4:5], s[10:11]
	v_mov_b64_e32 v[6:7], s[12:13]
	v_mov_b64_e32 v[8:9], s[14:15]
	v_mov_b64_e32 v[10:11], s[16:17]
	v_mov_b64_e32 v[12:13], s[18:19]
	v_mov_b64_e32 v[14:15], s[20:21]
	v_mov_b64_e32 v[16:17], s[22:23]
	s_nop 1
	s_waitcnt vmcnt(0) lgkmcnt(0)
	v_mfma_scale_f32_32x32x64_f8f6f4 v[18:33], v[18:25], v[176:183], v[2:17], v240, v239 op_sel_hi:[0,0,0]
	s_xor_b64 s[48:49], s[54:55], -1
	s_add_u32 s56, s56, s36
	s_addc_u32 s57, s57, 0
	v_lshl_add_u64 v[224:225], v[216:217], 0, s[58:59]
	v_lshl_add_u64 v[226:227], v[218:219], 0, s[56:57]
	s_mov_b32 s45, 0
	s_mov_b32 s47, 0
	v_mfma_scale_f32_32x32x64_f8f6f4 v[2:17], v[34:41], v[176:183], v[2:17], v240, v239 op_sel_hi:[0,0,0]
	ds_read_b128 v[38:41], v245 offset:32768
	ds_read_b128 v[34:37], v244 offset:32768
	ds_read_b128 v[42:45], v244 offset:36864
	ds_read_b128 v[46:49], v245 offset:36864
	s_waitcnt lgkmcnt(2)
	v_mfma_scale_f32_32x32x64_f8f6f4 v[18:33], v[34:41], v[184:191], v[18:33], v240, v239 op_sel_hi:[0,0,0]
	s_waitcnt lgkmcnt(0)
	v_mfma_scale_f32_32x32x64_f8f6f4 v[2:17], v[42:49], v[184:191], v[2:17], v240, v239 op_sel_hi:[0,0,0]
	s_nop 15
	s_nop 1
	v_max_f32_e32 v1, v19, v19
	v_max_f32_e32 v34, v18, v18
	v_max_f32_e32 v1, v34, v1
	v_max3_f32 v1, v1, v20, v21
	v_max3_f32 v1, v1, v22, v23
	v_max3_f32 v1, v1, v24, v25
	v_max3_f32 v1, v1, v26, v27
	v_max3_f32 v1, v1, v28, v29
	v_max3_f32 v1, v1, v30, v31
	v_max3_f32 v1, v1, v32, v33
	v_max3_f32 v1, v1, v2, v3
	v_max3_f32 v1, v1, v4, v5
	v_max3_f32 v1, v1, v6, v7
	v_max3_f32 v1, v1, v8, v9
	v_max3_f32 v1, v1, v10, v11
	v_max3_f32 v1, v1, v12, v13
	v_max3_f32 v1, v1, v14, v15
	v_max3_f32 v1, v1, v16, v17
	v_mov_b32_e32 v34, v1
	s_nop 1
	v_permlane32_swap_b32_e32 v1, v34
	v_max_f32_e32 v34, v34, v34
	v_max_f32_e32 v1, v1, v1
	v_max_f32_e32 v1, v1, v34
	v_add_f32_e32 v1, 0xc0a00000, v1
	v_sub_f32_e32 v18, v18, v1
	v_sub_f32_e32 v19, v19, v1
	v_sub_f32_e32 v20, v20, v1
	v_sub_f32_e32 v21, v21, v1
	v_sub_f32_e32 v22, v22, v1
	v_sub_f32_e32 v23, v23, v1
	v_sub_f32_e32 v24, v24, v1
	v_sub_f32_e32 v25, v25, v1
	v_sub_f32_e32 v26, v26, v1
	v_sub_f32_e32 v27, v27, v1
	v_sub_f32_e32 v28, v28, v1
	v_sub_f32_e32 v29, v29, v1
	v_sub_f32_e32 v30, v30, v1
	v_sub_f32_e32 v31, v31, v1
	v_sub_f32_e32 v32, v32, v1
	v_sub_f32_e32 v33, v33, v1
	v_exp_f32_e32 v144, v18
	v_exp_f32_e32 v145, v19
	v_exp_f32_e32 v146, v20
	v_exp_f32_e32 v147, v21
	v_exp_f32_e32 v148, v22
	v_exp_f32_e32 v149, v23
	v_exp_f32_e32 v150, v24
	v_exp_f32_e32 v151, v25
	v_exp_f32_e32 v152, v26
	v_exp_f32_e32 v153, v27
	v_exp_f32_e32 v154, v28
	v_exp_f32_e32 v155, v29
	v_exp_f32_e32 v156, v30
	v_exp_f32_e32 v157, v31
	v_exp_f32_e32 v158, v32
	v_exp_f32_e32 v159, v33
	v_sub_f32_e32 v125, v15, v1
	v_sub_f32_e32 v124, v14, v1
	v_mov_b32_e32 v14, v0
	v_mov_b32_e32 v15, v0
	v_sub_f32_e32 v96, 0x40a00000, v1
	v_sub_f32_e32 v127, v17, v1
	v_sub_f32_e32 v126, v16, v1
	v_sub_f32_e32 v123, v13, v1
	v_sub_f32_e32 v122, v12, v1
	v_sub_f32_e32 v121, v11, v1
	v_sub_f32_e32 v120, v10, v1
	v_sub_f32_e32 v119, v9, v1
	v_sub_f32_e32 v118, v8, v1
	v_sub_f32_e32 v117, v7, v1
	v_sub_f32_e32 v116, v6, v1
	v_sub_f32_e32 v115, v5, v1
	v_sub_f32_e32 v114, v4, v1
	v_sub_f32_e32 v113, v3, v1
	v_sub_f32_e32 v112, v2, v1
	v_mov_b32_e32 v1, v0
	v_mov_b32_e32 v2, v0
	v_mov_b32_e32 v3, v0
	v_mov_b32_e32 v4, v0
	v_mov_b32_e32 v5, v0
	v_mov_b32_e32 v6, v0
	v_mov_b32_e32 v7, v0
	v_mov_b32_e32 v8, v0
	v_mov_b32_e32 v9, v0
	v_mov_b32_e32 v10, v0
	v_mov_b32_e32 v11, v0
	v_mov_b32_e32 v12, v0
	v_mov_b32_e32 v13, v0
	v_mov_b64_e32 v[78:79], v[14:15]
	v_mov_b64_e32 v[62:63], v[14:15]
	v_mov_b64_e32 v[46:47], v[14:15]
	v_mov_b64_e32 v[30:31], v[14:15]
	v_mov_b64_e32 v[94:95], v[14:15]
	v_mov_b32_e32 v97, v96
	v_mov_b32_e32 v98, v96
	v_mov_b32_e32 v99, v96
	v_mov_b32_e32 v100, v96
	v_mov_b32_e32 v101, v96
	v_mov_b32_e32 v102, v96
	v_mov_b32_e32 v103, v96
	v_mov_b32_e32 v104, v96
	v_mov_b32_e32 v105, v96
	v_mov_b32_e32 v106, v96
	v_mov_b32_e32 v107, v96
	v_mov_b32_e32 v108, v96
	v_mov_b32_e32 v109, v96
	v_mov_b32_e32 v110, v96
	v_mov_b32_e32 v111, v96
	v_mov_b64_e32 v[76:77], v[12:13]
	v_mov_b64_e32 v[74:75], v[10:11]
	v_mov_b64_e32 v[72:73], v[8:9]
	v_mov_b64_e32 v[70:71], v[6:7]
	v_mov_b64_e32 v[68:69], v[4:5]
	v_mov_b64_e32 v[66:67], v[2:3]
	v_mov_b64_e32 v[64:65], v[0:1]
	v_mov_b64_e32 v[60:61], v[12:13]
	v_mov_b64_e32 v[58:59], v[10:11]
	v_mov_b64_e32 v[56:57], v[8:9]
	v_mov_b64_e32 v[54:55], v[6:7]
	v_mov_b64_e32 v[52:53], v[4:5]
	v_mov_b64_e32 v[50:51], v[2:3]
	v_mov_b64_e32 v[48:49], v[0:1]
	v_mov_b64_e32 v[44:45], v[12:13]
	v_mov_b64_e32 v[42:43], v[10:11]
	v_mov_b64_e32 v[40:41], v[8:9]
	v_mov_b64_e32 v[38:39], v[6:7]
	v_mov_b64_e32 v[36:37], v[4:5]
	v_mov_b64_e32 v[34:35], v[2:3]
	v_mov_b64_e32 v[32:33], v[0:1]
	v_mov_b64_e32 v[28:29], v[12:13]
	v_mov_b64_e32 v[26:27], v[10:11]
	v_mov_b64_e32 v[24:25], v[8:9]
	v_mov_b64_e32 v[22:23], v[6:7]
	v_mov_b64_e32 v[20:21], v[4:5]
	v_mov_b64_e32 v[18:19], v[2:3]
	v_mov_b64_e32 v[16:17], v[0:1]
	v_mov_b64_e32 v[92:93], v[12:13]
	v_mov_b64_e32 v[90:91], v[10:11]
	v_mov_b64_e32 v[88:89], v[8:9]
	v_mov_b64_e32 v[86:87], v[6:7]
	v_mov_b64_e32 v[84:85], v[4:5]
	v_mov_b64_e32 v[82:83], v[2:3]
	v_mov_b64_e32 v[80:81], v[0:1]
	s_cmp_lg_u32 s92, 0
	s_cbranch_scc0 .LBB0_374
	s_setprio 1
	s_branch .LgB_374
	s_branch .LBB0_374

; #define SBAR() __builtin_amdgcn_sched_barrier(0)
; #define DMA(slot, t) do { \
;     __builtin_amdgcn_global_load_lds((const unsigned*)(Kg + (long)(t) * (64 * 256)), (LAS unsigned*)(L3 + K_OFF + (slot) * SHM_T + wid * 1024), 16, 0, 0); \
;     __builtin_amdgcn_global_load_lds((const unsigned*)(Vg + (long)(t) * 8192), (LAS unsigned*)(L3 + (slot) * SHM_T + wid * 1024), 16, 0, 0); } while (0)
; #define QKT(P0, P1, b) qkt(P0, P1, nm, K_lds + (b) * SHM_T, qr, ko, c00, c01, c10, c11)
; #define PIPE1() do { SGB(0x100, 8); SGB(0x400, 4); SGB(0x008, 1); SGB(0x400, 4); SGB(0x008, 1); SGB(0x400, 4); SGB(0x008, 1); SGB(0x400, 4); SGB(0x008, 1); } while (0)
; #define HALF2(Y0, Y1, alY, b) do { PVL(b); const float pm_ = max32(Y0, Y1); adjustSM(Y0, Y1, nm, alY, pm_); SBAR(); \
;     PVM(); exp16(Y0); asm volatile("" : "+v"(Y0)); \
;     SGB(0x008, 1); SGB(0x400, 3); SGB(0x008, 1); SGB(0x400, 3); SGB(0x008, 1); SGB(0x400, 3); SGB(0x008, 1); SGB(0x400, 3); SGB(0x008, 1); SGB(0x400, 4); SBAR(); } while (0)
; __device__ __forceinline__ void body(const unsigned char* Q8b, const unsigned char* K8h, const unsigned char* VT8h, const bf16_t* Gb, bf16_t* Ob, int seq, char* lds, const int wid, ...
;     ...
;     SBAR(); QKT(pB0, pB1, (s0 + 1) & 3);
;     finishSM(pA0, pA1, pf); PIPE1(); SBAR();
;     DMA((s0 + 3) & 3, i + 3);
;     SBAR();
;     HALF2(pB0, pB1, alB, s0);
.LBB0_374:
	ds_read_b128 v[2:5], v242 offset:40960
	ds_read_b128 v[6:9], v243 offset:40960
	ds_read_b128 v[128:131], v242 offset:45056
	ds_read_b128 v[132:135], v243 offset:45056
	ds_read_b128 v[194:197], v244 offset:40960
	ds_read_b128 v[198:201], v245 offset:40960
	ds_read_b128 v[246:249], v244 offset:45056
	ds_read_b128 v[250:253], v245 offset:45056
	v_exp_f32_e32 v1, v112
	v_exp_f32_e32 v10, v113
	v_exp_f32_e32 v11, v114
	v_exp_f32_e32 v12, v115
	s_waitcnt lgkmcnt(6)
	v_mfma_scale_f32_32x32x64_f8f6f4 v[160:175], v[2:9], v[176:183], v[96:111], v240, v239 op_sel_hi:[0,0,0]
	v_exp_f32_e32 v6, v116
	v_exp_f32_e32 v7, v117
	v_exp_f32_e32 v8, v118
	v_exp_f32_e32 v9, v119
	v_cvt_pk_fp8_f32 v5, v6, v7
	v_cvt_pk_fp8_f32 v3, v1, v10
	v_cvt_pk_fp8_f32 v5, v8, v9 op_sel:[0,0,1]
	s_waitcnt lgkmcnt(4)
	v_mfma_scale_f32_32x32x64_f8f6f4 v[128:143], v[128:135], v[176:183], v[96:111], v240, v239 op_sel_hi:[0,0,0]
	v_exp_f32_e32 v13, v120
	v_exp_f32_e32 v14, v121
	v_exp_f32_e32 v15, v122
	v_exp_f32_e32 v112, v123
	v_cvt_pk_fp8_f32 v2, v144, v145
	v_cvt_pk_fp8_f32 v4, v148, v149
	v_cvt_pk_fp8_f32 v6, v152, v153
	v_cvt_pk_fp8_f32 v7, v13, v14
	v_cvt_pk_fp8_f32 v8, v156, v157
	v_cvt_pk_fp8_f32 v2, v146, v147 op_sel:[0,0,1]
	v_cvt_pk_fp8_f32 v3, v11, v12 op_sel:[0,0,1]
	v_cvt_pk_fp8_f32 v4, v150, v151 op_sel:[0,0,1]
	v_cvt_pk_fp8_f32 v6, v154, v155 op_sel:[0,0,1]
	v_cvt_pk_fp8_f32 v7, v15, v112 op_sel:[0,0,1]
	v_cvt_pk_fp8_f32 v8, v158, v159 op_sel:[0,0,1]
	s_waitcnt lgkmcnt(2)
	v_mfma_scale_f32_32x32x64_f8f6f4 v[160:175], v[194:201], v[184:191], v[160:175], v240, v239 op_sel_hi:[0,0,0]
	v_exp_f32_e32 v113, v124
	v_exp_f32_e32 v114, v125
	v_exp_f32_e32 v1, v126
	v_exp_f32_e32 v10, v127
	v_cvt_pk_fp8_f32 v9, v113, v114
	s_waitcnt lgkmcnt(0)
	v_cvt_pk_fp8_f32 v9, v1, v10 op_sel:[0,0,1]
	v_mfma_scale_f32_32x32x64_f8f6f4 v[128:143], v[246:253], v[184:191], v[128:143], v240, v239 op_sel_hi:[0,0,0]
	s_add_i32 m0, s68, 0xe000
	ds_read_b128 v[194:197], v254
	global_load_lds_dwordx4 v192, s[98:99]
	s_add_i32 m0, s68, 0x6000
	ds_read_b128 v[148:151], v254 offset:2048
	global_load_lds_dwordx4 v193, s[100:101]
	ds_read_b128 v[198:201], v255
	ds_read_b128 v[152:155], v255 offset:2048
	ds_read_b128 v[120:123], v254 offset:4096
	ds_read_b128 v[112:115], v254 offset:6144
	ds_read_b128 v[124:127], v255 offset:4096
	ds_read_b128 v[116:119], v255 offset:6144
	v_max_f32_e32 v1, v160, v161
	v_max3_f32 v1, v1, v162, v163
	v_max3_f32 v1, v1, v164, v165
	v_max3_f32 v1, v1, v166, v167
	v_max3_f32 v1, v1, v168, v169
	v_max3_f32 v1, v1, v170, v171
	v_max3_f32 v1, v1, v172, v173
	v_max3_f32 v1, v1, v174, v175
	v_max3_f32 v1, v1, v128, v129
	v_max3_f32 v1, v1, v130, v131
	v_max3_f32 v1, v1, v132, v133
	v_max3_f32 v1, v1, v134, v135
	v_max3_f32 v1, v1, v136, v137
	v_max3_f32 v1, v1, v138, v139
	v_max3_f32 v1, v1, v140, v141
	v_max3_f32 v1, v1, v142, v143
	v_cmp_lt_f32_e32 vcc, s80, v1
	s_cbranch_vccnz .LBB0_383

; #define SBAR() __builtin_amdgcn_sched_barrier(0)
; #define DMA(slot, t) do { \
;     __builtin_amdgcn_global_load_lds((const unsigned*)(Kg + (long)(t) * (64 * 256)), (LAS unsigned*)(L3 + K_OFF + (slot) * SHM_T + wid * 1024), 16, 0, 0); \
;     __builtin_amdgcn_global_load_lds((const unsigned*)(Vg + (long)(t) * 8192), (LAS unsigned*)(L3 + (slot) * SHM_T + wid * 1024), 16, 0, 0); } while (0)
; #define BAR() do { asm volatile("s_waitcnt lgkmcnt(0)" ::: "memory"); __builtin_amdgcn_s_barrier(); asm volatile("" ::: "memory"); } while (0)
; #define RESC(a) do { if (__any((a) < 1.f)) { if (hi == 0) al_l[r32] = (a); asm volatile("s_waitcnt lgkmcnt(0)" ::: "memory"); \
;     for (int r = 0; r < 16; ++r) { const float a_ = al_l[crow(r, hi)]; ls[r] *= a_; for (int d = 0; d < 4; ++d) o[d][r] *= a_; } } } while (0)
; #define QKT(P0, P1, b) qkt(P0, P1, nm, K_lds + (b) * SHM_T, qr, ko, c00, c01, c10, c11)
; #define PIPE1() do { SGB(0x100, 8); SGB(0x400, 4); SGB(0x008, 1); SGB(0x400, 4); SGB(0x008, 1); SGB(0x400, 4); SGB(0x008, 1); SGB(0x400, 4); SGB(0x008, 1); } while (0)
; #define HALF2(Y0, Y1, alY, b) do { PVL(b); const float pm_ = max32(Y0, Y1); adjustSM(Y0, Y1, nm, alY, pm_); SBAR(); \
;     PVM(); exp16(Y0); asm volatile("" : "+v"(Y0)); \
;     SGB(0x008, 1); SGB(0x400, 3); SGB(0x008, 1); SGB(0x400, 3); SGB(0x008, 1); SGB(0x400, 3); SGB(0x008, 1); SGB(0x400, 3); SGB(0x008, 1); SGB(0x400, 4); SBAR(); } while (0)
; __device__ __forceinline__ void body(const unsigned char* Q8b, const unsigned char* K8h, const unsigned char* VT8h, const bf16_t* Gb, bf16_t* Ob, int seq, char* lds, const int wid, ...
;     ...
;     RESC(alB); BAR();
;     SBAR(); QKT(pA0, pA1, (s0 + 2) & 3);
;     finishSM(pB0, pB1, pf); PIPE1(); SBAR();
;     { const int t4 = (i + 4 < NT) ? i + 4 : NT - 1; DMA(s0, t4); }
;     SBAR();
;     HALF2(pA0, pA1, alA, (s0 + 1) & 3);
.LBB0_379:
	s_waitcnt lgkmcnt(0)
	s_barrier
	ds_read_b128 v[2:5], v242 offset:49152
	ds_read_b128 v[6:9], v243 offset:49152
	ds_read_b128 v[112:115], v242 offset:53248
	ds_read_b128 v[116:119], v243 offset:53248
	ds_read_b128 v[194:197], v244 offset:49152
	ds_read_b128 v[198:201], v245 offset:49152
	ds_read_b128 v[246:249], v244 offset:53248
	ds_read_b128 v[250:253], v245 offset:53248
	v_exp_f32_e32 v1, v128
	v_exp_f32_e32 v10, v129
	v_exp_f32_e32 v11, v130
	v_exp_f32_e32 v12, v131
	s_waitcnt lgkmcnt(6)
	v_mfma_scale_f32_32x32x64_f8f6f4 v[160:175], v[2:9], v[176:183], v[96:111], v240, v239 op_sel_hi:[0,0,0]
	v_exp_f32_e32 v6, v132
	v_exp_f32_e32 v7, v133
	v_exp_f32_e32 v8, v134
	v_exp_f32_e32 v9, v135
	v_cvt_pk_fp8_f32 v5, v6, v7
	v_cvt_pk_fp8_f32 v2, v144, v145
	v_cvt_pk_fp8_f32 v5, v8, v9 op_sel:[0,0,1]
	s_waitcnt lgkmcnt(4)
	v_mfma_scale_f32_32x32x64_f8f6f4 v[112:127], v[112:119], v[176:183], v[96:111], v240, v239 op_sel_hi:[0,0,0]
	v_exp_f32_e32 v13, v136
	v_exp_f32_e32 v14, v137
	v_exp_f32_e32 v15, v138
	v_exp_f32_e32 v128, v139
	v_cvt_pk_fp8_f32 v3, v1, v10
	v_cvt_pk_fp8_f32 v4, v148, v149
	v_cvt_pk_fp8_f32 v6, v152, v153
	v_cvt_pk_fp8_f32 v7, v13, v14
	v_cvt_pk_fp8_f32 v8, v156, v157
	v_cvt_pk_fp8_f32 v2, v146, v147 op_sel:[0,0,1]
	v_cvt_pk_fp8_f32 v3, v11, v12 op_sel:[0,0,1]
	v_cvt_pk_fp8_f32 v4, v150, v151 op_sel:[0,0,1]
	v_cvt_pk_fp8_f32 v6, v154, v155 op_sel:[0,0,1]
	v_cvt_pk_fp8_f32 v7, v15, v128 op_sel:[0,0,1]
	v_cvt_pk_fp8_f32 v8, v158, v159 op_sel:[0,0,1]
	s_waitcnt lgkmcnt(2)
	v_mfma_scale_f32_32x32x64_f8f6f4 v[160:175], v[194:201], v[184:191], v[160:175], v240, v239 op_sel_hi:[0,0,0]
	v_exp_f32_e32 v129, v140
	v_exp_f32_e32 v130, v141
	v_exp_f32_e32 v131, v142
	v_exp_f32_e32 v132, v143
	v_cvt_pk_fp8_f32 v9, v129, v130
	s_waitcnt lgkmcnt(0)
	v_cvt_pk_fp8_f32 v9, v131, v132 op_sel:[0,0,1]
	v_mfma_scale_f32_32x32x64_f8f6f4 v[112:127], v[246:253], v[184:191], v[112:127], v240, v239 op_sel_hi:[0,0,0]
	s_min_u32 s36, s45, 0x7b
	s_add_i32 s56, s36, 4
	s_lshl_b32 s36, s56, 14
	s_add_i32 s57, s68, 0x0
	s_add_u32 s88, s94, s36
	s_addc_u32 s89, s95, 0
	s_add_i32 m0, s57, 0x8000
	s_lshl_b32 s36, s56, 13
	s_add_u32 s90, s96, s36
	s_addc_u32 s91, s97, 0
	global_load_lds_dwordx4 v192, s[88:89]
	s_mov_b32 m0, s57
	ds_read_b128 v[194:197], v254 offset:8192
	global_load_lds_dwordx4 v193, s[90:91]
	ds_read_b128 v[148:151], v254 offset:10240
	ds_read_b128 v[198:201], v255 offset:8192
	ds_read_b128 v[152:155], v255 offset:10240
	ds_read_b128 v[136:139], v254 offset:12288
	ds_read_b128 v[128:131], v254 offset:14336
	ds_read_b128 v[140:143], v255 offset:12288
	ds_read_b128 v[132:135], v255 offset:14336
	v_max_f32_e32 v1, v160, v161
	v_max3_f32 v1, v1, v162, v163
	v_max3_f32 v1, v1, v164, v165
	v_max3_f32 v1, v1, v166, v167
	v_max3_f32 v1, v1, v168, v169
	v_max3_f32 v1, v1, v170, v171
	v_max3_f32 v1, v1, v172, v173
	v_max3_f32 v1, v1, v174, v175
	v_max3_f32 v1, v1, v112, v113
	v_max3_f32 v1, v1, v114, v115
	v_max3_f32 v1, v1, v116, v117
	v_max3_f32 v1, v1, v118, v119
	v_max3_f32 v1, v1, v120, v121
	v_max3_f32 v1, v1, v122, v123
	v_max3_f32 v1, v1, v124, v125
	v_max3_f32 v1, v1, v126, v127
	v_cmp_lt_f32_e32 vcc, s80, v1
	s_cbranch_vccnz .LBB0_384

; #define SBAR() __builtin_amdgcn_sched_barrier(0)
; #define DMA(slot, t) do { \
;     __builtin_amdgcn_global_load_lds((const unsigned*)(Kg + (long)(t) * (64 * 256)), (LAS unsigned*)(L3 + K_OFF + (slot) * SHM_T + wid * 1024), 16, 0, 0); \
;     __builtin_amdgcn_global_load_lds((const unsigned*)(Vg + (long)(t) * 8192), (LAS unsigned*)(L3 + (slot) * SHM_T + wid * 1024), 16, 0, 0); } while (0)
; #define QKT(P0, P1, b) qkt(P0, P1, nm, K_lds + (b) * SHM_T, qr, ko, c00, c01, c10, c11)
; #define PIPE1() do { SGB(0x100, 8); SGB(0x400, 4); SGB(0x008, 1); SGB(0x400, 4); SGB(0x008, 1); SGB(0x400, 4); SGB(0x008, 1); SGB(0x400, 4); SGB(0x008, 1); } while (0)
; #define HALF2(Y0, Y1, alY, b) do { PVL(b); const float pm_ = max32(Y0, Y1); adjustSM(Y0, Y1, nm, alY, pm_); SBAR(); \
;     PVM(); exp16(Y0); asm volatile("" : "+v"(Y0)); \
;     SGB(0x008, 1); SGB(0x400, 3); SGB(0x008, 1); SGB(0x400, 3); SGB(0x008, 1); SGB(0x400, 3); SGB(0x008, 1); SGB(0x400, 3); SGB(0x008, 1); SGB(0x400, 4); SBAR(); } while (0)
; __device__ __forceinline__ void body(const unsigned char* Q8b, const unsigned char* K8h, const unsigned char* VT8h, const bf16_t* Gb, bf16_t* Ob, int seq, char* lds, const int wid, ...
;     ...
;     SBAR(); QKT(pB0, pB1, (s0 + 1) & 3);
;     finishSM(pA0, pA1, pf); PIPE1(); SBAR();
;     DMA((s0 + 3) & 3, i + 3);
;     SBAR();
;     HALF2(pB0, pB1, alB, s0);
.Lc2_374:
	ds_read_b128 v[2:5], v242 offset:57344
	ds_read_b128 v[6:9], v243 offset:57344
	ds_read_b128 v[128:131], v242 offset:61440
	ds_read_b128 v[132:135], v243 offset:61440
	ds_read_b128 v[194:197], v244 offset:57344
	ds_read_b128 v[198:201], v245 offset:57344
	ds_read_b128 v[246:249], v244 offset:61440
	ds_read_b128 v[250:253], v245 offset:61440
	v_exp_f32_e32 v1, v112
	v_exp_f32_e32 v10, v113
	v_exp_f32_e32 v11, v114
	v_exp_f32_e32 v12, v115
	s_waitcnt lgkmcnt(6)
	v_mfma_scale_f32_32x32x64_f8f6f4 v[160:175], v[2:9], v[176:183], v[96:111], v240, v239 op_sel_hi:[0,0,0]
	v_exp_f32_e32 v6, v116
	v_exp_f32_e32 v7, v117
	v_exp_f32_e32 v8, v118
	v_exp_f32_e32 v9, v119
	v_cvt_pk_fp8_f32 v5, v6, v7
	v_cvt_pk_fp8_f32 v3, v1, v10
	v_cvt_pk_fp8_f32 v5, v8, v9 op_sel:[0,0,1]
	s_waitcnt lgkmcnt(4)
	v_mfma_scale_f32_32x32x64_f8f6f4 v[128:143], v[128:135], v[176:183], v[96:111], v240, v239 op_sel_hi:[0,0,0]
	v_exp_f32_e32 v13, v120
	v_exp_f32_e32 v14, v121
	v_exp_f32_e32 v15, v122
	v_exp_f32_e32 v112, v123
	v_cvt_pk_fp8_f32 v2, v144, v145
	v_cvt_pk_fp8_f32 v4, v148, v149
	v_cvt_pk_fp8_f32 v6, v152, v153
	v_cvt_pk_fp8_f32 v7, v13, v14
	v_cvt_pk_fp8_f32 v8, v156, v157
	v_cvt_pk_fp8_f32 v2, v146, v147 op_sel:[0,0,1]
	v_cvt_pk_fp8_f32 v3, v11, v12 op_sel:[0,0,1]
	v_cvt_pk_fp8_f32 v4, v150, v151 op_sel:[0,0,1]
	v_cvt_pk_fp8_f32 v6, v154, v155 op_sel:[0,0,1]
	v_cvt_pk_fp8_f32 v7, v15, v112 op_sel:[0,0,1]
	v_cvt_pk_fp8_f32 v8, v158, v159 op_sel:[0,0,1]
	s_waitcnt lgkmcnt(2)
	v_mfma_scale_f32_32x32x64_f8f6f4 v[160:175], v[194:201], v[184:191], v[160:175], v240, v239 op_sel_hi:[0,0,0]
	v_exp_f32_e32 v113, v124
	v_exp_f32_e32 v114, v125
	v_exp_f32_e32 v1, v126
	v_exp_f32_e32 v10, v127
	v_cvt_pk_fp8_f32 v9, v113, v114
	s_waitcnt lgkmcnt(0)
	v_cvt_pk_fp8_f32 v9, v1, v10 op_sel:[0,0,1]
	v_mfma_scale_f32_32x32x64_f8f6f4 v[128:143], v[246:253], v[184:191], v[128:143], v240, v239 op_sel_hi:[0,0,0]
	s_add_i32 m0, s68, 0xa000
	ds_read_b128 v[194:197], v254 offset:16384
	global_load_lds_dwordx4 v192, s[98:99]
	s_add_i32 m0, s68, 0x2000
	ds_read_b128 v[148:151], v254 offset:18432
	global_load_lds_dwordx4 v193, s[100:101]
	ds_read_b128 v[198:201], v255 offset:16384
	ds_read_b128 v[152:155], v255 offset:18432
	ds_read_b128 v[120:123], v254 offset:20480
	ds_read_b128 v[112:115], v254 offset:22528
	ds_read_b128 v[124:127], v255 offset:20480
	ds_read_b128 v[116:119], v255 offset:22528
	v_max_f32_e32 v1, v160, v161
	v_max3_f32 v1, v1, v162, v163
	v_max3_f32 v1, v1, v164, v165
	v_max3_f32 v1, v1, v166, v167
	v_max3_f32 v1, v1, v168, v169
	v_max3_f32 v1, v1, v170, v171
	v_max3_f32 v1, v1, v172, v173
	v_max3_f32 v1, v1, v174, v175
	v_max3_f32 v1, v1, v128, v129
	v_max3_f32 v1, v1, v130, v131
	v_max3_f32 v1, v1, v132, v133
	v_max3_f32 v1, v1, v134, v135
	v_max3_f32 v1, v1, v136, v137
	v_max3_f32 v1, v1, v138, v139
	v_max3_f32 v1, v1, v140, v141
	v_max3_f32 v1, v1, v142, v143
	v_cmp_lt_f32_e32 vcc, s80, v1
	s_cbranch_vccnz .Lc2_383

; #define SBAR() __builtin_amdgcn_sched_barrier(0)
; #define DMA(slot, t) do { \
;     __builtin_amdgcn_global_load_lds((const unsigned*)(Kg + (long)(t) * (64 * 256)), (LAS unsigned*)(L3 + K_OFF + (slot) * SHM_T + wid * 1024), 16, 0, 0); \
;     __builtin_amdgcn_global_load_lds((const unsigned*)(Vg + (long)(t) * 8192), (LAS unsigned*)(L3 + (slot) * SHM_T + wid * 1024), 16, 0, 0); } while (0)
; #define BAR() do { asm volatile("s_waitcnt lgkmcnt(0)" ::: "memory"); __builtin_amdgcn_s_barrier(); asm volatile("" ::: "memory"); } while (0)
; #define RESC(a) do { if (__any((a) < 1.f)) { if (hi == 0) al_l[r32] = (a); asm volatile("s_waitcnt lgkmcnt(0)" ::: "memory"); \
;     for (int r = 0; r < 16; ++r) { const float a_ = al_l[crow(r, hi)]; ls[r] *= a_; for (int d = 0; d < 4; ++d) o[d][r] *= a_; } } } while (0)
; #define QKT(P0, P1, b) qkt(P0, P1, nm, K_lds + (b) * SHM_T, qr, ko, c00, c01, c10, c11)
; #define PIPE1() do { SGB(0x100, 8); SGB(0x400, 4); SGB(0x008, 1); SGB(0x400, 4); SGB(0x008, 1); SGB(0x400, 4); SGB(0x008, 1); SGB(0x400, 4); SGB(0x008, 1); } while (0)
; #define HALF2(Y0, Y1, alY, b) do { PVL(b); const float pm_ = max32(Y0, Y1); adjustSM(Y0, Y1, nm, alY, pm_); SBAR(); \
;     PVM(); exp16(Y0); asm volatile("" : "+v"(Y0)); \
;     SGB(0x008, 1); SGB(0x400, 3); SGB(0x008, 1); SGB(0x400, 3); SGB(0x008, 1); SGB(0x400, 3); SGB(0x008, 1); SGB(0x400, 3); SGB(0x008, 1); SGB(0x400, 4); SBAR(); } while (0)
; __device__ __forceinline__ void body(const unsigned char* Q8b, const unsigned char* K8h, const unsigned char* VT8h, const bf16_t* Gb, bf16_t* Ob, int seq, char* lds, const int wid, ...
;     ...
;     RESC(alB); BAR();
;     SBAR(); QKT(pA0, pA1, (s0 + 2) & 3);
;     finishSM(pB0, pB1, pf); PIPE1(); SBAR();
;     { const int t4 = (i + 4 < NT) ? i + 4 : NT - 1; DMA(s0, t4); }
;     SBAR();
;     HALF2(pA0, pA1, alA, (s0 + 1) & 3);
.Lc2_379:
	s_waitcnt lgkmcnt(0)
	s_barrier
	ds_read_b128 v[2:5], v242 offset:32768
	ds_read_b128 v[6:9], v243 offset:32768
	ds_read_b128 v[112:115], v242 offset:36864
	ds_read_b128 v[116:119], v243 offset:36864
	ds_read_b128 v[194:197], v244 offset:32768
	ds_read_b128 v[198:201], v245 offset:32768
	ds_read_b128 v[246:249], v244 offset:36864
	ds_read_b128 v[250:253], v245 offset:36864
	v_exp_f32_e32 v1, v128
	v_exp_f32_e32 v10, v129
	v_exp_f32_e32 v11, v130
	v_exp_f32_e32 v12, v131
	s_waitcnt lgkmcnt(6)
	v_mfma_scale_f32_32x32x64_f8f6f4 v[160:175], v[2:9], v[176:183], v[96:111], v240, v239 op_sel_hi:[0,0,0]
	v_exp_f32_e32 v6, v132
	v_exp_f32_e32 v7, v133
	v_exp_f32_e32 v8, v134
	v_exp_f32_e32 v9, v135
	v_cvt_pk_fp8_f32 v5, v6, v7
	v_cvt_pk_fp8_f32 v2, v144, v145
	v_cvt_pk_fp8_f32 v5, v8, v9 op_sel:[0,0,1]
	s_waitcnt lgkmcnt(4)
	v_mfma_scale_f32_32x32x64_f8f6f4 v[112:127], v[112:119], v[176:183], v[96:111], v240, v239 op_sel_hi:[0,0,0]
	v_exp_f32_e32 v13, v136
	v_exp_f32_e32 v14, v137
	v_exp_f32_e32 v15, v138
	v_exp_f32_e32 v128, v139
	v_cvt_pk_fp8_f32 v3, v1, v10
	v_cvt_pk_fp8_f32 v4, v148, v149
	v_cvt_pk_fp8_f32 v6, v152, v153
	v_cvt_pk_fp8_f32 v7, v13, v14
	v_cvt_pk_fp8_f32 v8, v156, v157
	v_cvt_pk_fp8_f32 v2, v146, v147 op_sel:[0,0,1]
	v_cvt_pk_fp8_f32 v3, v11, v12 op_sel:[0,0,1]
	v_cvt_pk_fp8_f32 v4, v150, v151 op_sel:[0,0,1]
	v_cvt_pk_fp8_f32 v6, v154, v155 op_sel:[0,0,1]
	v_cvt_pk_fp8_f32 v7, v15, v128 op_sel:[0,0,1]
	v_cvt_pk_fp8_f32 v8, v158, v159 op_sel:[0,0,1]
	s_waitcnt lgkmcnt(2)
	v_mfma_scale_f32_32x32x64_f8f6f4 v[160:175], v[194:201], v[184:191], v[160:175], v240, v239 op_sel_hi:[0,0,0]
	v_exp_f32_e32 v129, v140
	v_exp_f32_e32 v130, v141
	v_exp_f32_e32 v131, v142
	v_exp_f32_e32 v132, v143
	v_cvt_pk_fp8_f32 v9, v129, v130
	s_waitcnt lgkmcnt(0)
	v_cvt_pk_fp8_f32 v9, v131, v132 op_sel:[0,0,1]
	v_mfma_scale_f32_32x32x64_f8f6f4 v[112:127], v[246:253], v[184:191], v[112:127], v240, v239 op_sel_hi:[0,0,0]
	s_min_u32 s36, s45, 0x7b
	s_add_i32 s56, s36, 4
	s_lshl_b32 s36, s56, 14
	s_add_i32 s57, s68, 0x4000
	s_add_u32 s88, s94, s36
	s_addc_u32 s89, s95, 0
	s_add_i32 m0, s57, 0x8000
	s_lshl_b32 s36, s56, 13
	s_add_u32 s90, s96, s36
	s_addc_u32 s91, s97, 0
	global_load_lds_dwordx4 v192, s[88:89]
	s_mov_b32 m0, s57
	ds_read_b128 v[194:197], v254 offset:24576
	global_load_lds_dwordx4 v193, s[90:91]
	ds_read_b128 v[148:151], v254 offset:26624
	ds_read_b128 v[198:201], v255 offset:24576
	ds_read_b128 v[152:155], v255 offset:26624
	ds_read_b128 v[136:139], v254 offset:28672
	ds_read_b128 v[128:131], v254 offset:30720
	ds_read_b128 v[140:143], v255 offset:28672
	ds_read_b128 v[132:135], v255 offset:30720
	v_max_f32_e32 v1, v160, v161
	v_max3_f32 v1, v1, v162, v163
	v_max3_f32 v1, v1, v164, v165
	v_max3_f32 v1, v1, v166, v167
	v_max3_f32 v1, v1, v168, v169
	v_max3_f32 v1, v1, v170, v171
	v_max3_f32 v1, v1, v172, v173
	v_max3_f32 v1, v1, v174, v175
	v_max3_f32 v1, v1, v112, v113
	v_max3_f32 v1, v1, v114, v115
	v_max3_f32 v1, v1, v116, v117
	v_max3_f32 v1, v1, v118, v119
	v_max3_f32 v1, v1, v120, v121
	v_max3_f32 v1, v1, v122, v123
	v_max3_f32 v1, v1, v124, v125
	v_max3_f32 v1, v1, v126, v127
	v_cmp_lt_f32_e32 vcc, s80, v1
	s_cbranch_vccnz .Lc2_384

; #define SBAR() __builtin_amdgcn_sched_barrier(0)
; #define DMA(slot, t) do { \
;     __builtin_amdgcn_global_load_lds((const unsigned*)(Kg + (long)(t) * (64 * 256)), (LAS unsigned*)(L3 + K_OFF + (slot) * SHM_T + wid * 1024), 16, 0, 0); \
;     __builtin_amdgcn_global_load_lds((const unsigned*)(Vg + (long)(t) * 8192), (LAS unsigned*)(L3 + (slot) * SHM_T + wid * 1024), 16, 0, 0); } while (0)
; #define BAR() do { asm volatile("s_waitcnt lgkmcnt(0)" ::: "memory"); __builtin_amdgcn_s_barrier(); asm volatile("" ::: "memory"); } while (0)
; #define RESC(a) do { if (__any((a) < 1.f)) { if (hi == 0) al_l[r32] = (a); asm volatile("s_waitcnt lgkmcnt(0)" ::: "memory"); \
;     for (int r = 0; r < 16; ++r) { const float a_ = al_l[crow(r, hi)]; ls[r] *= a_; for (int d = 0; d < 4; ++d) o[d][r] *= a_; } } } while (0)
; #define QKT(P0, P1, b) qkt(P0, P1, nm, K_lds + (b) * SHM_T, qr, ko, c00, c01, c10, c11)
; #define PIPE1() do { SGB(0x100, 8); SGB(0x400, 4); SGB(0x008, 1); SGB(0x400, 4); SGB(0x008, 1); SGB(0x400, 4); SGB(0x008, 1); SGB(0x400, 4); SGB(0x008, 1); } while (0)
; #define HALF2(Y0, Y1, alY, b) do { PVL(b); const float pm_ = max32(Y0, Y1); adjustSM(Y0, Y1, nm, alY, pm_); SBAR(); \
;     PVM(); exp16(Y0); asm volatile("" : "+v"(Y0)); \
;     SGB(0x008, 1); SGB(0x400, 3); SGB(0x008, 1); SGB(0x400, 3); SGB(0x008, 1); SGB(0x400, 3); SGB(0x008, 1); SGB(0x400, 3); SGB(0x008, 1); SGB(0x400, 4); SBAR(); } while (0)
; __device__ __forceinline__ void body(const unsigned char* Q8b, const unsigned char* K8h, const unsigned char* VT8h, const bf16_t* Gb, bf16_t* Ob, int seq, char* lds, const int wid, ...
;     ...
;     RESC(alB); BAR();
;     SBAR(); QKT(pA0, pA1, (s0 + 2) & 3);
;     finishSM(pB0, pB1, pf); PIPE1(); SBAR();
;     { const int t4 = (i + 4 < NT) ? i + 4 : NT - 1; DMA(s0, t4); }
;     SBAR();
;     HALF2(pA0, pA1, alA, (s0 + 1) & 3);
.LgB_379:
	ds_read_b128 v[2:5], v242 offset:49152
	ds_read_b128 v[6:9], v243 offset:49152
	ds_read_b128 v[112:115], v242 offset:53248
	ds_read_b128 v[116:119], v243 offset:53248
	ds_read_b128 v[194:197], v244 offset:49152
	ds_read_b128 v[198:201], v245 offset:49152
	ds_read_b128 v[246:249], v244 offset:53248
	ds_read_b128 v[250:253], v245 offset:53248
	v_exp_f32_e32 v1, v128
	v_exp_f32_e32 v10, v129
	v_exp_f32_e32 v11, v130
	v_exp_f32_e32 v12, v131
	s_waitcnt lgkmcnt(6)
	v_mfma_scale_f32_32x32x64_f8f6f4 v[160:175], v[2:9], v[176:183], v[96:111], v240, v239 op_sel_hi:[0,0,0]
	v_exp_f32_e32 v6, v132
	v_exp_f32_e32 v7, v133
	v_exp_f32_e32 v8, v134
	v_exp_f32_e32 v9, v135
	v_cvt_pk_fp8_f32 v5, v6, v7
	v_cvt_pk_fp8_f32 v2, v144, v145
	v_cvt_pk_fp8_f32 v5, v8, v9 op_sel:[0,0,1]
	s_waitcnt lgkmcnt(4)
	v_mfma_scale_f32_32x32x64_f8f6f4 v[112:127], v[112:119], v[176:183], v[96:111], v240, v239 op_sel_hi:[0,0,0]
	v_exp_f32_e32 v13, v136
	v_exp_f32_e32 v14, v137
	v_exp_f32_e32 v15, v138
	v_exp_f32_e32 v128, v139
	v_cvt_pk_fp8_f32 v3, v1, v10
	v_cvt_pk_fp8_f32 v4, v148, v149
	v_cvt_pk_fp8_f32 v6, v152, v153
	v_cvt_pk_fp8_f32 v7, v13, v14
	v_cvt_pk_fp8_f32 v8, v156, v157
	v_cvt_pk_fp8_f32 v2, v146, v147 op_sel:[0,0,1]
	v_cvt_pk_fp8_f32 v3, v11, v12 op_sel:[0,0,1]
	v_cvt_pk_fp8_f32 v4, v150, v151 op_sel:[0,0,1]
	v_cvt_pk_fp8_f32 v6, v154, v155 op_sel:[0,0,1]
	v_cvt_pk_fp8_f32 v7, v15, v128 op_sel:[0,0,1]
	v_cvt_pk_fp8_f32 v8, v158, v159 op_sel:[0,0,1]
	s_waitcnt lgkmcnt(2)
	v_mfma_scale_f32_32x32x64_f8f6f4 v[160:175], v[194:201], v[184:191], v[160:175], v240, v239 op_sel_hi:[0,0,0]
	v_exp_f32_e32 v129, v140
	v_exp_f32_e32 v130, v141
	v_exp_f32_e32 v131, v142
	v_exp_f32_e32 v132, v143
	v_cvt_pk_fp8_f32 v9, v129, v130
	s_waitcnt lgkmcnt(0)
	v_cvt_pk_fp8_f32 v9, v131, v132 op_sel:[0,0,1]
	v_mfma_scale_f32_32x32x64_f8f6f4 v[112:127], v[246:253], v[184:191], v[112:127], v240, v239 op_sel_hi:[0,0,0]
	s_min_u32 s36, s45, 0x7b
	s_add_i32 s56, s36, 4
	s_lshl_b32 s36, s56, 14
	s_add_i32 s57, s68, 0x0
	s_add_u32 s88, s94, s36
	s_addc_u32 s89, s95, 0
	s_add_i32 m0, s57, 0x8000
	s_lshl_b32 s36, s56, 13
	s_add_u32 s90, s96, s36
	s_addc_u32 s91, s97, 0
	global_load_lds_dwordx4 v192, s[88:89]
	s_mov_b32 m0, s57
	ds_read_b128 v[194:197], v254 offset:8192
	global_load_lds_dwordx4 v193, s[90:91]
	ds_read_b128 v[148:151], v254 offset:10240
	ds_read_b128 v[198:201], v255 offset:8192
	ds_read_b128 v[152:155], v255 offset:10240
	ds_read_b128 v[136:139], v254 offset:12288
	ds_read_b128 v[128:131], v254 offset:14336
	ds_read_b128 v[140:143], v255 offset:12288
	ds_read_b128 v[132:135], v255 offset:14336
	v_max_f32_e32 v1, v160, v161
	v_max3_f32 v1, v1, v162, v163
	v_max3_f32 v1, v1, v164, v165
	v_max3_f32 v1, v1, v166, v167
	v_max3_f32 v1, v1, v168, v169
	v_max3_f32 v1, v1, v170, v171
	v_max3_f32 v1, v1, v172, v173
	v_max3_f32 v1, v1, v174, v175
	v_max3_f32 v1, v1, v112, v113
	v_max3_f32 v1, v1, v114, v115
	v_max3_f32 v1, v1, v116, v117
	v_max3_f32 v1, v1, v118, v119
	v_max3_f32 v1, v1, v120, v121
	v_max3_f32 v1, v1, v122, v123
	v_max3_f32 v1, v1, v124, v125
	v_max3_f32 v1, v1, v126, v127
	v_cmp_lt_f32_e32 vcc, s80, v1
	s_cbranch_vccnz .LgB_384

; #define SBAR() __builtin_amdgcn_sched_barrier(0)
; #define DMA(slot, t) do { \
;     __builtin_amdgcn_global_load_lds((const unsigned*)(Kg + (long)(t) * (64 * 256)), (LAS unsigned*)(L3 + K_OFF + (slot) * SHM_T + wid * 1024), 16, 0, 0); \
;     __builtin_amdgcn_global_load_lds((const unsigned*)(Vg + (long)(t) * 8192), (LAS unsigned*)(L3 + (slot) * SHM_T + wid * 1024), 16, 0, 0); } while (0)
; #define BAR() do { asm volatile("s_waitcnt lgkmcnt(0)" ::: "memory"); __builtin_amdgcn_s_barrier(); asm volatile("" ::: "memory"); } while (0)
; #define RESC(a) do { if (__any((a) < 1.f)) { if (hi == 0) al_l[r32] = (a); asm volatile("s_waitcnt lgkmcnt(0)" ::: "memory"); \
;     for (int r = 0; r < 16; ++r) { const float a_ = al_l[crow(r, hi)]; ls[r] *= a_; for (int d = 0; d < 4; ++d) o[d][r] *= a_; } } } while (0)
; #define QKT(P0, P1, b) qkt(P0, P1, nm, K_lds + (b) * SHM_T, qr, ko, c00, c01, c10, c11)
; #define PIPE1() do { SGB(0x100, 8); SGB(0x400, 4); SGB(0x008, 1); SGB(0x400, 4); SGB(0x008, 1); SGB(0x400, 4); SGB(0x008, 1); SGB(0x400, 4); SGB(0x008, 1); } while (0)
; #define HALF2(Y0, Y1, alY, b) do { PVL(b); const float pm_ = max32(Y0, Y1); adjustSM(Y0, Y1, nm, alY, pm_); SBAR(); \
;     PVM(); exp16(Y0); asm volatile("" : "+v"(Y0)); \
;     SGB(0x008, 1); SGB(0x400, 3); SGB(0x008, 1); SGB(0x400, 3); SGB(0x008, 1); SGB(0x400, 3); SGB(0x008, 1); SGB(0x400, 3); SGB(0x008, 1); SGB(0x400, 4); SBAR(); } while (0)
; __device__ __forceinline__ void body(const unsigned char* Q8b, const unsigned char* K8h, const unsigned char* VT8h, const bf16_t* Gb, bf16_t* Ob, int seq, char* lds, const int wid, ...
;     ...
;     RESC(alB); BAR();
;     SBAR(); QKT(pA0, pA1, (s0 + 2) & 3);
;     finishSM(pB0, pB1, pf); PIPE1(); SBAR();
;     { const int t4 = (i + 4 < NT) ? i + 4 : NT - 1; DMA(s0, t4); }
;     SBAR();
;     HALF2(pA0, pA1, alA, (s0 + 1) & 3);
.LgBc2_379:
	ds_read_b128 v[2:5], v242 offset:32768
	ds_read_b128 v[6:9], v243 offset:32768
	ds_read_b128 v[112:115], v242 offset:36864
	ds_read_b128 v[116:119], v243 offset:36864
	ds_read_b128 v[194:197], v244 offset:32768
	ds_read_b128 v[198:201], v245 offset:32768
	ds_read_b128 v[246:249], v244 offset:36864
	ds_read_b128 v[250:253], v245 offset:36864
	v_exp_f32_e32 v1, v128
	v_exp_f32_e32 v10, v129
	v_exp_f32_e32 v11, v130
	v_exp_f32_e32 v12, v131
	s_waitcnt lgkmcnt(6)
	v_mfma_scale_f32_32x32x64_f8f6f4 v[160:175], v[2:9], v[176:183], v[96:111], v240, v239 op_sel_hi:[0,0,0]
	v_exp_f32_e32 v6, v132
	v_exp_f32_e32 v7, v133
	v_exp_f32_e32 v8, v134
	v_exp_f32_e32 v9, v135
	v_cvt_pk_fp8_f32 v5, v6, v7
	v_cvt_pk_fp8_f32 v2, v144, v145
	v_cvt_pk_fp8_f32 v5, v8, v9 op_sel:[0,0,1]
	s_waitcnt lgkmcnt(4)
	v_mfma_scale_f32_32x32x64_f8f6f4 v[112:127], v[112:119], v[176:183], v[96:111], v240, v239 op_sel_hi:[0,0,0]
	v_exp_f32_e32 v13, v136
	v_exp_f32_e32 v14, v137
	v_exp_f32_e32 v15, v138
	v_exp_f32_e32 v128, v139
	v_cvt_pk_fp8_f32 v3, v1, v10
	v_cvt_pk_fp8_f32 v4, v148, v149
	v_cvt_pk_fp8_f32 v6, v152, v153
	v_cvt_pk_fp8_f32 v7, v13, v14
	v_cvt_pk_fp8_f32 v8, v156, v157
	v_cvt_pk_fp8_f32 v2, v146, v147 op_sel:[0,0,1]
	v_cvt_pk_fp8_f32 v3, v11, v12 op_sel:[0,0,1]
	v_cvt_pk_fp8_f32 v4, v150, v151 op_sel:[0,0,1]
	v_cvt_pk_fp8_f32 v6, v154, v155 op_sel:[0,0,1]
	v_cvt_pk_fp8_f32 v7, v15, v128 op_sel:[0,0,1]
	v_cvt_pk_fp8_f32 v8, v158, v159 op_sel:[0,0,1]
	s_waitcnt lgkmcnt(2)
	v_mfma_scale_f32_32x32x64_f8f6f4 v[160:175], v[194:201], v[184:191], v[160:175], v240, v239 op_sel_hi:[0,0,0]
	v_exp_f32_e32 v129, v140
	v_exp_f32_e32 v130, v141
	v_exp_f32_e32 v131, v142
	v_exp_f32_e32 v132, v143
	v_cvt_pk_fp8_f32 v9, v129, v130
	s_waitcnt lgkmcnt(0)
	v_cvt_pk_fp8_f32 v9, v131, v132 op_sel:[0,0,1]
	v_mfma_scale_f32_32x32x64_f8f6f4 v[112:127], v[246:253], v[184:191], v[112:127], v240, v239 op_sel_hi:[0,0,0]
	s_min_u32 s36, s45, 0x7b
	s_add_i32 s56, s36, 4
	s_lshl_b32 s36, s56, 14
	s_add_i32 s57, s68, 0x4000
	s_add_u32 s88, s94, s36
	s_addc_u32 s89, s95, 0
	s_add_i32 m0, s57, 0x8000
	s_lshl_b32 s36, s56, 13
	s_add_u32 s90, s96, s36
	s_addc_u32 s91, s97, 0
	global_load_lds_dwordx4 v192, s[88:89]
	s_mov_b32 m0, s57
	ds_read_b128 v[194:197], v254 offset:24576
	global_load_lds_dwordx4 v193, s[90:91]
	ds_read_b128 v[148:151], v254 offset:26624
	ds_read_b128 v[198:201], v255 offset:24576
	ds_read_b128 v[152:155], v255 offset:26624
	ds_read_b128 v[136:139], v254 offset:28672
	ds_read_b128 v[128:131], v254 offset:30720
	ds_read_b128 v[140:143], v255 offset:28672
	ds_read_b128 v[132:135], v255 offset:30720
	v_max_f32_e32 v1, v160, v161
	v_max3_f32 v1, v1, v162, v163
	v_max3_f32 v1, v1, v164, v165
	v_max3_f32 v1, v1, v166, v167
	v_max3_f32 v1, v1, v168, v169
	v_max3_f32 v1, v1, v170, v171
	v_max3_f32 v1, v1, v172, v173
	v_max3_f32 v1, v1, v174, v175
	v_max3_f32 v1, v1, v112, v113
	v_max3_f32 v1, v1, v114, v115
	v_max3_f32 v1, v1, v116, v117
	v_max3_f32 v1, v1, v118, v119
	v_max3_f32 v1, v1, v120, v121
	v_max3_f32 v1, v1, v122, v123
	v_max3_f32 v1, v1, v124, v125
	v_max3_f32 v1, v1, v126, v127
	v_cmp_lt_f32_e32 vcc, s80, v1
	s_cbranch_vccnz .LgBc2_384

; #define SBAR() __builtin_amdgcn_sched_barrier(0)
; #define QKT(P0, P1, b) qkt(P0, P1, nm, K_lds + (b) * SHM_T, qr, ko, c00, c01, c10, c11)
; #define HALF2(Y0, Y1, alY, b) do { PVL(b); const float pm_ = max32(Y0, Y1); adjustSM(Y0, Y1, nm, alY, pm_); SBAR(); \
;     PVM(); exp16(Y0); asm volatile("" : "+v"(Y0)); \
;     SGB(0x008, 1); SGB(0x400, 3); SGB(0x008, 1); SGB(0x400, 3); SGB(0x008, 1); SGB(0x400, 3); SGB(0x008, 1); SGB(0x400, 3); SGB(0x008, 1); SGB(0x400, 4); SBAR(); } while (0)
; __device__ __forceinline__ void body(const unsigned char* Q8b, const unsigned char* K8h, const unsigned char* VT8h, const bf16_t* Gb, bf16_t* Ob, int seq, char* lds, const int wid, ...
;     ...
;   SBAR(); QKT(pB0, pB1, (s0 + 1) & 3);
;   finishSM(pA0, pA1, pf); SBAR();
;   HALF2(pB0, pB1, alB, s0);
.LBB0_385:
	s_setprio 0
	ds_read_b128 v[6:9], v243 offset:57344
	ds_read_b128 v[2:5], v242 offset:57344
	ds_read_b128 v[160:163], v242 offset:61440
	ds_read_b128 v[164:167], v243 offset:61440
	ds_read_b128 v[168:171], v244 offset:57344
	ds_read_b128 v[194:197], v244 offset:61440
	ds_read_b128 v[172:175], v245 offset:57344
	ds_read_b128 v[198:201], v245 offset:61440
	s_waitcnt lgkmcnt(0)
	v_mfma_scale_f32_32x32x64_f8f6f4 v[128:143], v[2:9], v[176:183], v[96:111], v240, v239 op_sel_hi:[0,0,0]
	v_exp_f32_e32 v1, v112
	v_exp_f32_e32 v10, v113
	v_mov_b32_e32 v3, v0
	v_exp_f32_e32 v6, v114
	v_exp_f32_e32 v7, v115
	v_exp_f32_e32 v8, v116
	v_exp_f32_e32 v9, v117
	v_cvt_pk_fp8_f32 v3, v1, v10
	v_exp_f32_e32 v13, v120
	v_exp_f32_e32 v14, v121
	v_exp_f32_e32 v113, v124
	v_exp_f32_e32 v114, v125
	v_mov_b32_e32 v5, v0
	v_mov_b32_e32 v2, v0
	v_mov_b32_e32 v4, v0
	v_mfma_scale_f32_32x32x64_f8f6f4 v[96:111], v[160:167], v[176:183], v[96:111], v240, v239 op_sel_hi:[0,0,0]
	v_cvt_pk_fp8_f32 v5, v8, v9
	v_cvt_pk_fp8_f32 v3, v6, v7 op_sel:[0,0,1]
	v_mov_b32_e32 v6, v0
	v_mov_b32_e32 v7, v0
	v_mov_b32_e32 v8, v0
	v_mov_b32_e32 v9, v0
	v_exp_f32_e32 v11, v118
	v_exp_f32_e32 v12, v119
	v_exp_f32_e32 v15, v122
	v_exp_f32_e32 v112, v123
	v_exp_f32_e32 v115, v126
	v_exp_f32_e32 v116, v127
	v_cvt_pk_fp8_f32 v2, v144, v145
	v_cvt_pk_fp8_f32 v4, v148, v149
	v_cvt_pk_fp8_f32 v6, v152, v153
	v_mfma_scale_f32_32x32x64_f8f6f4 v[128:143], v[168:175], v[184:191], v[128:143], v240, v239 op_sel_hi:[0,0,0]
	v_cvt_pk_fp8_f32 v7, v13, v14
	v_cvt_pk_fp8_f32 v8, v156, v157
	v_cvt_pk_fp8_f32 v9, v113, v114
	v_cvt_pk_fp8_f32 v2, v146, v147 op_sel:[0,0,1]
	v_cvt_pk_fp8_f32 v4, v150, v151 op_sel:[0,0,1]
	v_cvt_pk_fp8_f32 v5, v11, v12 op_sel:[0,0,1]
	v_cvt_pk_fp8_f32 v6, v154, v155 op_sel:[0,0,1]
	v_cvt_pk_fp8_f32 v7, v15, v112 op_sel:[0,0,1]
	v_cvt_pk_fp8_f32 v8, v158, v159 op_sel:[0,0,1]
	v_cvt_pk_fp8_f32 v9, v115, v116 op_sel:[0,0,1]
	s_nop 0
	v_mfma_scale_f32_32x32x64_f8f6f4 v[96:111], v[194:201], v[184:191], v[96:111], v240, v239 op_sel_hi:[0,0,0]
	s_nop 4
	v_max_f32_e32 v11, v129, v129
	v_max_f32_e32 v12, v128, v128
	v_max_f32_e32 v11, v12, v11
	v_max3_f32 v11, v11, v130, v131
	v_max3_f32 v11, v11, v132, v133
	v_max3_f32 v11, v11, v134, v135
	v_max3_f32 v11, v11, v136, v137
	v_max3_f32 v11, v11, v138, v139
	v_max3_f32 v11, v11, v140, v141
	v_max3_f32 v11, v11, v142, v143
	s_nop 3
	v_max3_f32 v11, v11, v96, v97
	v_mov_b32_e32 v1, v254
	v_max3_f32 v11, v11, v98, v99
	v_mov_b32_e32 v10, v255
	ds_read_b128 v[160:163], v1 offset:16384
	ds_read_b128 v[152:155], v1 offset:18432
	ds_read_b128 v[164:167], v10 offset:16384
	ds_read_b128 v[156:159], v10 offset:18432
	ds_read_b128 v[118:121], v1 offset:20480
	ds_read_b128 v[144:147], v1 offset:22528
	ds_read_b128 v[122:125], v10 offset:20480
	ds_read_b128 v[148:151], v10 offset:22528
	v_max3_f32 v11, v11, v100, v101
	v_max3_f32 v11, v11, v102, v103
	v_max3_f32 v11, v11, v104, v105
	v_max3_f32 v11, v11, v106, v107
	v_max3_f32 v11, v11, v108, v109
	v_max3_f32 v11, v11, v110, v111
	v_mov_b32_e32 v12, v11
	s_nop 1
	v_permlane32_swap_b32_e32 v11, v12
	v_max_f32_e32 v12, v12, v12
	v_max_f32_e32 v11, v11, v11
	v_max_f32_e32 v12, v11, v12
	v_cmp_lt_f32_e32 vcc, s80, v12
	v_mov_b32_e32 v11, 1.0
	s_cbranch_vccnz .LBB0_392
